# first grid barrier also takes the workgroup count from a register instead of loading it from the barrier struct
# baseline (speedup 1.0000x reference)
; __global__ void __launch_bounds__(256, 2) mega(P p, int ph_lo, int ph_hi) {
;     ...
;   cg::grid_group grid = cg::this_grid();
;   run_phase(p, 0, smem, &s_item);
;   grid.sync();
.LBB0_86:
	s_or_b64 exec, exec, s[4:5]
	v_lshrrev_b32_e32 v2, 20, v0
	v_lshrrev_b32_e32 v0, 10, v0
	v_or_b32_e32 v0, v0, v2
	s_movk_i32 s0, 0x3ff
	v_and_or_b32 v0, v0, s0, v220
	v_cmp_eq_u32_e64 s[28:29], 0, v0
	s_waitcnt lgkmcnt(0)
	s_barrier
	s_and_saveexec_b64 s[0:1], s[28:29]
	s_cbranch_execz .LBB0_96
	v_readlane_b32 s4, v252, 0
	v_readlane_b32 s5, v252, 1
	buffer_wbl2 sc1
	s_waitcnt vmcnt(0)
	s_load_dwordx2 s[4:5], s[4:5], 0x58
	v_mov_b32_e32 v3, 0
	s_mov_b64 s[6:7], exec
	v_mbcnt_lo_u32_b32 v2, s6, 0
	v_mbcnt_hi_u32_b32 v2, s7, v2
	s_waitcnt lgkmcnt(0)
	v_mov_b32_e32 v0, s60
	v_cmp_eq_u32_e32 vcc, 0, v2
	s_and_saveexec_b64 s[8:9], vcc
	s_cbranch_execz .LBB0_89
	s_bcnt1_i32_b64 s3, s[6:7]
	v_mov_b32_e32 v4, s3
	global_atomic_add v4, v3, v4, s[4:5] offset:32 sc0
